# adds: OUT phase half of workgroups start 8us late (epilogue bursts interleave); conv GLU staging loop issues all 8 loads of the 4 unrolled sub-iterations up front
# speedup vs baseline: 1.3711x; 1.0005x over previous
.LBB0_529:
	v_add_u32_e32 v2, v16, v28
	v_cmp_lt_u32_e64 s[2:3], v2, v7
	v_max_i32_e32 v2, 0, v2
	v_lshlrev_b32_e32 v0, 1, v23
	v_min_u32_e32 v2, v2, v15
	v_and_b32_e32 v30, 0x3f0, v0
	v_and_b32_e32 v0, 0x1f8, v18
	v_add_u32_e32 v2, v2, v14
	v_mov_b64_e32 v[12:13], s[42:43]
	v_mad_i64_i32 v[2:3], s[0:1], v2, s72, v[12:13]
	v_lshlrev_b32_e32 v0, 1, v0
	v_lshl_add_u64 v[34:35], v[2:3], 0, v[0:1]
	v_add_co_u32_e64 v2, s[0:1], s87, v34
	v_mov_b32_e32 v9, v1
	s_nop 0
	v_addc_co_u32_e64 v3, s[0:1], 0, v35, s[0:1]
	v_add_co_u32_e64 v34, s[0:1], s69, v34
	global_load_dwordx4 v[42:45], v[2:3], off offset:3072
	s_nop 0
	v_addc_co_u32_e64 v35, s[0:1], 0, v35, s[0:1]
	global_load_dwordx4 v[46:49], v[34:35], off
	v_add_u32_e32 v19, 0x400, v19
	v_add_u32_e32 v23, 0x2000, v23
	v_add_u32_e32 v28, 16, v28
	v_add_u32_e32 v0, v16, v26
	v_cmp_lt_u32_e64 s[78:79], v0, v7
	v_max_i32_e32 v0, 0, v0
	v_min_u32_e32 v0, v0, v15
	v_add_u32_e32 v0, v0, v14
	v_mad_i64_i32 v[2:3], s[0:1], v0, s72, v[12:13]
	v_lshl_add_u64 v[34:35], v[2:3], 0, v[8:9]
	v_add_co_u32_e64 v2, s[0:1], s87, v34
	v_add_u32_e32 v26, 16, v26
	s_nop 0
	v_addc_co_u32_e64 v3, s[0:1], 0, v35, s[0:1]
	v_add_co_u32_e64 v34, s[0:1], s69, v34
	global_load_dwordx4 v[50:53], v[2:3], off offset:3072
	s_nop 0
	v_addc_co_u32_e64 v35, s[0:1], 0, v35, s[0:1]
	global_load_dwordx4 v[54:57], v[34:35], off
	v_add_u32_e32 v2, v16, v24
	v_cmp_lt_u32_e64 s[98:99], v2, v7
	v_max_i32_e32 v2, 0, v2
	v_add_u32_e32 v0, 0x1000, v18
	v_min_u32_e32 v2, v2, v15
	v_and_b32_e32 v0, 0x1f8, v0
	v_add_u32_e32 v2, v2, v14
	v_mad_i64_i32 v[2:3], s[0:1], v2, s72, v[12:13]
	v_lshlrev_b32_e32 v0, 1, v0
	v_lshl_add_u64 v[34:35], v[2:3], 0, v[0:1]
	v_add_co_u32_e64 v2, s[0:1], s87, v34
	v_add_u32_e32 v18, 0x2000, v18
	s_nop 0
	v_addc_co_u32_e64 v3, s[0:1], 0, v35, s[0:1]
	v_add_co_u32_e64 v34, s[0:1], s69, v34
	global_load_dwordx4 v[58:61], v[2:3], off offset:3072
	s_nop 0
	v_addc_co_u32_e64 v35, s[0:1], 0, v35, s[0:1]
	global_load_dwordx4 v[62:65], v[34:35], off
	v_add_u32_e32 v24, 16, v24
	v_add_u32_e32 v0, v16, v21
	v_cmp_lt_u32_e64 s[100:101], v0, v7
	v_max_i32_e32 v0, 0, v0
	v_min_u32_e32 v0, v0, v15
	v_add_u32_e32 v0, v0, v14
	v_mad_i64_i32 v[2:3], s[0:1], v0, s72, v[12:13]
	v_lshl_add_u64 v[12:13], v[2:3], 0, v[8:9]
	v_add_co_u32_e64 v2, s[0:1], s87, v12
	v_add_u32_e32 v21, 16, v21
	s_nop 0
	v_addc_co_u32_e64 v3, s[0:1], 0, v13, s[0:1]
	v_add_co_u32_e64 v12, s[0:1], s69, v12
	global_load_dwordx4 v[66:69], v[2:3], off offset:3072
	s_nop 0
	v_addc_co_u32_e64 v13, s[0:1], 0, v13, s[0:1]
	global_load_dwordx4 v[70:73], v[12:13], off
	s_movk_i32 s0, 0xb7f
	s_waitcnt vmcnt(6)
	v_mov_b32_e32 v2, v42
	v_mov_b32_e32 v3, v43
	v_mov_b32_e32 v4, v44
	v_mov_b32_e32 v5, v45
	v_mov_b32_e32 v34, v46
	v_mov_b32_e32 v35, v47
	v_mov_b32_e32 v36, v48
	v_mov_b32_e32 v37, v49
	v_lshlrev_b32_e32 v40, 16, v2
	v_and_b32_e32 v41, 0xffff0000, v2
	v_lshlrev_b32_e32 v0, 16, v34
	v_mul_f32_e32 v0, 0xbfb8aa3b, v0
	v_exp_f32_e32 v0, v0
	s_nop 0
	v_add_f32_e32 v0, 1.0, v0
	v_rcp_f32_e32 v38, v0
	v_and_b32_e32 v0, 0xffff0000, v34
	v_mul_f32_e32 v0, 0xbfb8aa3b, v0
	v_exp_f32_e32 v0, v0
	s_nop 0
	v_add_f32_e32 v0, 1.0, v0
	v_rcp_f32_e32 v39, v0
	s_nop 0
	v_pk_mul_f32 v[38:39], v[38:39], v[40:41]
	s_nop 0
	v_cvt_pk_bf16_f32 v0, v38, v39
	v_cndmask_b32_e64 v2, 0, v0, s[2:3]
	v_lshlrev_b32_e32 v0, 16, v35
	v_mul_f32_e32 v0, 0xbfb8aa3b, v0
	v_exp_f32_e32 v0, v0
	v_lshlrev_b32_e32 v38, 16, v3
	v_and_b32_e32 v39, 0xffff0000, v3
	v_add_f32_e32 v0, 1.0, v0
	v_rcp_f32_e32 v34, v0
	v_and_b32_e32 v0, 0xffff0000, v35
	v_mul_f32_e32 v0, 0xbfb8aa3b, v0
	v_exp_f32_e32 v0, v0
	s_nop 0
	v_add_f32_e32 v0, 1.0, v0
	v_rcp_f32_e32 v35, v0
	s_nop 0
	v_pk_mul_f32 v[34:35], v[34:35], v[38:39]
	s_nop 0
	v_cvt_pk_bf16_f32 v0, v34, v35
	v_cndmask_b32_e64 v3, 0, v0, s[2:3]
	v_lshlrev_b32_e32 v0, 16, v36
	v_mul_f32_e32 v0, 0xbfb8aa3b, v0
	v_exp_f32_e32 v0, v0
	v_lshlrev_b32_e32 v38, 16, v4
	v_and_b32_e32 v39, 0xffff0000, v4
	v_add_f32_e32 v0, 1.0, v0
	v_rcp_f32_e32 v34, v0
	v_and_b32_e32 v0, 0xffff0000, v36
	v_mul_f32_e32 v0, 0xbfb8aa3b, v0
	v_exp_f32_e32 v0, v0
	v_lshlrev_b32_e32 v36, 16, v5
	v_add_f32_e32 v0, 1.0, v0
	v_rcp_f32_e32 v35, v0
	s_nop 0
	v_pk_mul_f32 v[34:35], v[34:35], v[38:39]
	s_nop 0
	v_cvt_pk_bf16_f32 v0, v34, v35
	v_cndmask_b32_e64 v4, 0, v0, s[2:3]
	v_lshlrev_b32_e32 v0, 16, v37
	v_mul_f32_e32 v0, 0xbfb8aa3b, v0
	v_exp_f32_e32 v0, v0
	s_nop 0
	v_add_f32_e32 v0, 1.0, v0
	v_rcp_f32_e32 v34, v0
	v_and_b32_e32 v0, 0xffff0000, v37
	v_mul_f32_e32 v0, 0xbfb8aa3b, v0
	v_exp_f32_e32 v0, v0
	v_and_b32_e32 v37, 0xffff0000, v5
	v_add_f32_e32 v0, 1.0, v0
	v_rcp_f32_e32 v35, v0
	s_nop 0
	v_pk_mul_f32 v[34:35], v[34:35], v[36:37]
	s_nop 0
	v_cvt_pk_bf16_f32 v0, v34, v35
	v_cndmask_b32_e64 v5, 0, v0, s[2:3]
	v_add_u32_e32 v0, v29, v27
	ds_write_b128 v0, v[2:5]
	s_waitcnt vmcnt(4)
	v_mov_b32_e32 v2, v50
	v_mov_b32_e32 v3, v51
	v_mov_b32_e32 v4, v52
	v_mov_b32_e32 v5, v53
	v_mov_b32_e32 v34, v54
	v_mov_b32_e32 v35, v55
	v_mov_b32_e32 v36, v56
	v_mov_b32_e32 v37, v57
	v_lshlrev_b32_e32 v40, 16, v2
	v_and_b32_e32 v41, 0xffff0000, v2
	v_lshlrev_b32_e32 v0, 16, v34
	v_mul_f32_e32 v0, 0xbfb8aa3b, v0
	v_exp_f32_e32 v0, v0
	s_nop 0
	v_add_f32_e32 v0, 1.0, v0
	v_rcp_f32_e32 v38, v0
	v_and_b32_e32 v0, 0xffff0000, v34
	v_mul_f32_e32 v0, 0xbfb8aa3b, v0
	v_exp_f32_e32 v0, v0
	s_nop 0
	v_add_f32_e32 v0, 1.0, v0
	v_rcp_f32_e32 v39, v0
	s_nop 0
	v_pk_mul_f32 v[38:39], v[38:39], v[40:41]
	s_nop 0
	v_cvt_pk_bf16_f32 v0, v38, v39
	v_cndmask_b32_e64 v2, 0, v0, s[78:79]
	v_lshlrev_b32_e32 v0, 16, v35
	v_mul_f32_e32 v0, 0xbfb8aa3b, v0
	v_exp_f32_e32 v0, v0
	v_lshlrev_b32_e32 v38, 16, v3
	v_and_b32_e32 v39, 0xffff0000, v3
	v_add_f32_e32 v0, 1.0, v0
	v_rcp_f32_e32 v34, v0
	v_and_b32_e32 v0, 0xffff0000, v35
	v_mul_f32_e32 v0, 0xbfb8aa3b, v0
	v_exp_f32_e32 v0, v0
	s_nop 0
	v_add_f32_e32 v0, 1.0, v0
	v_rcp_f32_e32 v35, v0
	s_nop 0
	v_pk_mul_f32 v[34:35], v[34:35], v[38:39]
	s_nop 0
	v_cvt_pk_bf16_f32 v0, v34, v35
	v_cndmask_b32_e64 v3, 0, v0, s[78:79]
	v_lshlrev_b32_e32 v0, 16, v36
	v_mul_f32_e32 v0, 0xbfb8aa3b, v0
	v_exp_f32_e32 v0, v0
	v_lshlrev_b32_e32 v38, 16, v4
	v_and_b32_e32 v39, 0xffff0000, v4
	v_add_f32_e32 v0, 1.0, v0
	v_rcp_f32_e32 v34, v0
	v_and_b32_e32 v0, 0xffff0000, v36
	v_mul_f32_e32 v0, 0xbfb8aa3b, v0
	v_exp_f32_e32 v0, v0
	v_lshlrev_b32_e32 v36, 16, v5
	v_add_f32_e32 v0, 1.0, v0
	v_rcp_f32_e32 v35, v0
	s_nop 0
	v_pk_mul_f32 v[34:35], v[34:35], v[38:39]
	s_nop 0
	v_cvt_pk_bf16_f32 v0, v34, v35
	v_cndmask_b32_e64 v4, 0, v0, s[78:79]
	v_lshlrev_b32_e32 v0, 16, v37
	v_mul_f32_e32 v0, 0xbfb8aa3b, v0
	v_exp_f32_e32 v0, v0
	s_nop 0
	v_add_f32_e32 v0, 1.0, v0
	v_rcp_f32_e32 v34, v0
	v_and_b32_e32 v0, 0xffff0000, v37
	v_mul_f32_e32 v0, 0xbfb8aa3b, v0
	v_exp_f32_e32 v0, v0
	v_and_b32_e32 v37, 0xffff0000, v5
	v_add_f32_e32 v0, 1.0, v0
	v_rcp_f32_e32 v35, v0
	s_nop 0
	v_pk_mul_f32 v[34:35], v[34:35], v[36:37]
	s_nop 0
	v_cvt_pk_bf16_f32 v0, v34, v35
	v_cndmask_b32_e64 v5, 0, v0, s[78:79]
	v_add_u32_e32 v0, v29, v25
	ds_write_b128 v0, v[2:5]
	s_waitcnt vmcnt(2)
	v_mov_b32_e32 v2, v58
	v_mov_b32_e32 v3, v59
	v_mov_b32_e32 v4, v60
	v_mov_b32_e32 v5, v61
	v_mov_b32_e32 v34, v62
	v_mov_b32_e32 v35, v63
	v_mov_b32_e32 v36, v64
	v_mov_b32_e32 v37, v65
	v_lshlrev_b32_e32 v40, 16, v2
	v_and_b32_e32 v41, 0xffff0000, v2
	v_lshlrev_b32_e32 v0, 16, v34
	v_mul_f32_e32 v0, 0xbfb8aa3b, v0
	v_exp_f32_e32 v0, v0
	s_nop 0
	v_add_f32_e32 v0, 1.0, v0
	v_rcp_f32_e32 v38, v0
	v_and_b32_e32 v0, 0xffff0000, v34
	v_mul_f32_e32 v0, 0xbfb8aa3b, v0
	v_exp_f32_e32 v0, v0
	s_nop 0
	v_add_f32_e32 v0, 1.0, v0
	v_rcp_f32_e32 v39, v0
	s_nop 0
	v_pk_mul_f32 v[38:39], v[38:39], v[40:41]
	s_nop 0
	v_cvt_pk_bf16_f32 v0, v38, v39
	v_cndmask_b32_e64 v2, 0, v0, s[98:99]
	v_lshlrev_b32_e32 v0, 16, v35
	v_mul_f32_e32 v0, 0xbfb8aa3b, v0
	v_exp_f32_e32 v0, v0
	v_lshlrev_b32_e32 v38, 16, v3
	v_and_b32_e32 v39, 0xffff0000, v3
	v_add_f32_e32 v0, 1.0, v0
	v_rcp_f32_e32 v34, v0
	v_and_b32_e32 v0, 0xffff0000, v35
	v_mul_f32_e32 v0, 0xbfb8aa3b, v0
	v_exp_f32_e32 v0, v0
	s_nop 0
	v_add_f32_e32 v0, 1.0, v0
	v_rcp_f32_e32 v35, v0
	s_nop 0
	v_pk_mul_f32 v[34:35], v[34:35], v[38:39]
	s_nop 0
	v_cvt_pk_bf16_f32 v0, v34, v35
	v_cndmask_b32_e64 v3, 0, v0, s[98:99]
	v_lshlrev_b32_e32 v0, 16, v36
	v_mul_f32_e32 v0, 0xbfb8aa3b, v0
	v_exp_f32_e32 v0, v0
	v_lshlrev_b32_e32 v38, 16, v4
	v_and_b32_e32 v39, 0xffff0000, v4
	v_add_f32_e32 v0, 1.0, v0
	v_rcp_f32_e32 v34, v0
	v_and_b32_e32 v0, 0xffff0000, v36
	v_mul_f32_e32 v0, 0xbfb8aa3b, v0
	v_exp_f32_e32 v0, v0
	v_lshlrev_b32_e32 v36, 16, v5
	v_add_f32_e32 v0, 1.0, v0
	v_rcp_f32_e32 v35, v0
	s_nop 0
	v_pk_mul_f32 v[34:35], v[34:35], v[38:39]
	s_nop 0
	v_cvt_pk_bf16_f32 v0, v34, v35
	v_cndmask_b32_e64 v4, 0, v0, s[98:99]
	v_lshlrev_b32_e32 v0, 16, v37
	v_mul_f32_e32 v0, 0xbfb8aa3b, v0
	v_exp_f32_e32 v0, v0
	s_nop 0
	v_add_f32_e32 v0, 1.0, v0
	v_rcp_f32_e32 v34, v0
	v_and_b32_e32 v0, 0xffff0000, v37
	v_mul_f32_e32 v0, 0xbfb8aa3b, v0
	v_exp_f32_e32 v0, v0
	v_and_b32_e32 v37, 0xffff0000, v5
	v_add_f32_e32 v0, 1.0, v0
	v_rcp_f32_e32 v35, v0
	s_nop 0
	v_pk_mul_f32 v[34:35], v[34:35], v[36:37]
	s_nop 0
	v_cvt_pk_bf16_f32 v0, v34, v35
	v_cndmask_b32_e64 v5, 0, v0, s[98:99]
	v_add3_u32 v0, v29, v22, v30
	ds_write_b128 v0, v[2:5]
	s_waitcnt vmcnt(0)
	v_mov_b32_e32 v2, v66
	v_mov_b32_e32 v3, v67
	v_mov_b32_e32 v4, v68
	v_mov_b32_e32 v5, v69
	v_mov_b32_e32 v34, v70
	v_mov_b32_e32 v35, v71
	v_mov_b32_e32 v36, v72
	v_mov_b32_e32 v37, v73
	v_lshlrev_b32_e32 v30, 16, v2
	v_and_b32_e32 v31, 0xffff0000, v2
	v_lshlrev_b32_e32 v0, 16, v34
	v_mul_f32_e32 v0, 0xbfb8aa3b, v0
	v_exp_f32_e32 v0, v0
	s_nop 0
	v_add_f32_e32 v0, 1.0, v0
	v_rcp_f32_e32 v12, v0
	v_and_b32_e32 v0, 0xffff0000, v34
	v_mul_f32_e32 v0, 0xbfb8aa3b, v0
	v_exp_f32_e32 v0, v0
	s_nop 0
	v_add_f32_e32 v0, 1.0, v0
	v_rcp_f32_e32 v13, v0
	s_nop 0
	v_pk_mul_f32 v[12:13], v[12:13], v[30:31]
	s_nop 0
	v_cvt_pk_bf16_f32 v0, v12, v13
	v_cndmask_b32_e64 v2, 0, v0, s[100:101]
	v_lshlrev_b32_e32 v0, 16, v35
	v_mul_f32_e32 v0, 0xbfb8aa3b, v0
	v_exp_f32_e32 v0, v0
	v_lshlrev_b32_e32 v30, 16, v3
	v_and_b32_e32 v31, 0xffff0000, v3
	v_add_f32_e32 v0, 1.0, v0
	v_rcp_f32_e32 v12, v0
	v_and_b32_e32 v0, 0xffff0000, v35
	v_mul_f32_e32 v0, 0xbfb8aa3b, v0
	v_exp_f32_e32 v0, v0
	s_nop 0
	v_add_f32_e32 v0, 1.0, v0
	v_rcp_f32_e32 v13, v0
	s_nop 0
	v_pk_mul_f32 v[12:13], v[12:13], v[30:31]
	s_nop 0
	v_cvt_pk_bf16_f32 v0, v12, v13
	v_cndmask_b32_e64 v3, 0, v0, s[100:101]
	v_lshlrev_b32_e32 v0, 16, v36
	v_mul_f32_e32 v0, 0xbfb8aa3b, v0
	v_exp_f32_e32 v0, v0
	v_lshlrev_b32_e32 v30, 16, v4
	v_and_b32_e32 v31, 0xffff0000, v4
	v_add_f32_e32 v0, 1.0, v0
	v_rcp_f32_e32 v12, v0
	v_and_b32_e32 v0, 0xffff0000, v36
	v_mul_f32_e32 v0, 0xbfb8aa3b, v0
	v_exp_f32_e32 v0, v0
	s_nop 0
	v_add_f32_e32 v0, 1.0, v0
	v_rcp_f32_e32 v13, v0
	s_nop 0
	v_pk_mul_f32 v[12:13], v[12:13], v[30:31]
	s_nop 0
	v_cvt_pk_bf16_f32 v0, v12, v13
	v_cndmask_b32_e64 v4, 0, v0, s[100:101]
	v_lshlrev_b32_e32 v0, 16, v37
	v_mul_f32_e32 v0, 0xbfb8aa3b, v0
	v_exp_f32_e32 v0, v0
	v_lshlrev_b32_e32 v30, 16, v5
	v_and_b32_e32 v31, 0xffff0000, v5
	v_add_f32_e32 v0, 1.0, v0
	v_rcp_f32_e32 v12, v0
	v_and_b32_e32 v0, 0xffff0000, v37
	v_mul_f32_e32 v0, 0xbfb8aa3b, v0
	v_exp_f32_e32 v0, v0
	s_nop 0
	v_add_f32_e32 v0, 1.0, v0
	v_rcp_f32_e32 v13, v0
	s_nop 0
	v_pk_mul_f32 v[12:13], v[12:13], v[30:31]
	s_nop 0
	v_cvt_pk_bf16_f32 v0, v12, v13
	v_cndmask_b32_e64 v5, 0, v0, s[100:101]
	v_cmp_lt_u32_e32 vcc, s0, v19
	v_add_u32_e32 v0, v29, v20
	v_add_u32_e32 v29, 0x4000, v29
	s_or_b64 s[4:5], vcc, s[4:5]
	ds_write_b128 v0, v[2:5]
	s_andn2_b64 exec, exec, s[4:5]
	s_cbranch_execnz .LBB0_529
	s_or_b64 exec, exec, s[4:5]
	v_readlane_b32 s0, v255, 17
	v_readlane_b32 s1, v255, 18
	s_waitcnt lgkmcnt(0)
	s_barrier
	v_readlane_b32 s2, v255, 26
	v_mov_b32_e32 v7, v1
	s_nop 0
	global_load_dwordx2 v[12:13], v6, s[0:1]
	v_readlane_b32 s0, v255, 19
	v_readlane_b32 s1, v255, 20
	v_readlane_b32 s3, v255, 27
	v_lshlrev_b32_e32 v0, 1, v11
	v_lshl_add_u32 v34, v11, 2, v17
	v_lshl_add_u64 v[2:3], s[2:3], 0, v[6:7]
	s_waitcnt vmcnt(0)
	v_mov_b32_e32 v15, v13
	global_load_dwordx2 v[8:9], v6, s[0:1]
	s_mov_b32 s0, 0
	v_mov_b32_e32 v17, v13
	v_mov_b32_e32 v19, v13
	v_mov_b32_e32 v21, v13
	v_mov_b32_e32 v23, v13
	v_mov_b32_e32 v25, v13
	v_mov_b32_e32 v27, v13
	v_mov_b32_e32 v29, v13
	v_mov_b32_e32 v31, v13
	v_mov_b32_e32 v39, v13
	v_mov_b32_e32 v41, v13
	v_mov_b32_e32 v43, v13
	v_mov_b32_e32 v45, v13
	v_mov_b32_e32 v47, v13
	v_mov_b32_e32 v49, v13
	v_mov_b32_e32 v51, v13
	v_mov_b32_e32 v53, v13
	v_mov_b32_e32 v55, v13
	v_mov_b32_e32 v57, v13
	v_mov_b32_e32 v59, v13
	v_mov_b32_e32 v61, v13
	v_mov_b32_e32 v63, v13
	v_mov_b32_e32 v65, v13
	v_mov_b32_e32 v67, v13
	v_mov_b32_e32 v69, v13
	v_mov_b32_e32 v71, v13
	v_mov_b32_e32 v73, v13
	v_mov_b32_e32 v75, v13
	v_mov_b32_e32 v77, v13
	v_mov_b32_e32 v79, v13
	v_mov_b32_e32 v81, v13
	v_mov_b32_e32 v80, v12
	v_mov_b32_e32 v78, v12
	v_mov_b32_e32 v76, v12
	v_mov_b32_e32 v74, v12
	v_mov_b32_e32 v72, v12
	v_mov_b32_e32 v70, v12
	v_mov_b32_e32 v68, v12
	v_mov_b32_e32 v66, v12
	v_mov_b32_e32 v64, v12
	v_mov_b32_e32 v62, v12
	v_mov_b32_e32 v60, v12
	v_mov_b32_e32 v58, v12
	v_mov_b32_e32 v56, v12
	v_mov_b32_e32 v54, v12
	v_mov_b32_e32 v52, v12
	v_mov_b32_e32 v50, v12
	v_mov_b32_e32 v48, v12
	v_mov_b32_e32 v46, v12
	v_mov_b32_e32 v44, v12
	v_mov_b32_e32 v42, v12
	v_mov_b32_e32 v40, v12
	v_mov_b32_e32 v38, v12
	v_mov_b32_e32 v30, v12
	v_mov_b32_e32 v28, v12
	v_mov_b32_e32 v26, v12
	v_mov_b32_e32 v24, v12
	v_mov_b32_e32 v22, v12
	v_mov_b32_e32 v20, v12
	v_mov_b32_e32 v18, v12
	v_mov_b32_e32 v16, v12
	v_mov_b32_e32 v14, v12
	s_waitcnt vmcnt(0)
	v_mov_b64_e32 v[4:5], v[8:9]
	s_cmpk_eq_i32 s0, 0x7800
	s_cbranch_scc1 .LBB0_533
	s_branch .LBB0_532

.LBB0_799:
	s_or_b64 exec, exec, s[0:1]
	v_readlane_b32 s0, v255, 1
	v_readlane_b32 s1, v255, 2
	s_andn2_b64 vcc, exec, s[0:1]
	s_waitcnt lgkmcnt(0)
	s_barrier
	s_cbranch_vccnz .LBB0_848
	v_readlane_b32 s98, v254, 0
	s_bfe_u32 s98, s98, 0x10003
	s_cmp_eq_u32 s98, 0
	s_cbranch_scc1 .Lout_nodelay
	s_mov_b32 s98, 2
.Lout_delay:
	s_sleep 127
	s_sub_u32 s98, s98, 1
	s_cmp_lg_u32 s98, 0
	s_cbranch_scc1 .Lout_delay
.Lout_nodelay:
	s_lshl_b32 s0, s46, 23
	v_readlane_b32 s1, v255, 3
	s_add_u32 s30, s1, s0
	v_readlane_b32 s0, v255, 4
	s_addc_u32 s31, s0, 0
	v_readlane_b32 s46, v254, 0
	s_branch .LBB0_802

	.amdhsa_kernel _Z14fwd_megakernel6Params
		.amdhsa_group_segment_fixed_size 16
		.amdhsa_private_segment_fixed_size 0
		.amdhsa_kernarg_size 456
		.amdhsa_user_sgpr_count 2
		.amdhsa_user_sgpr_dispatch_ptr 0
		.amdhsa_user_sgpr_queue_ptr 0
		.amdhsa_user_sgpr_kernarg_segment_ptr 1
		.amdhsa_user_sgpr_dispatch_id 0
		.amdhsa_user_sgpr_kernarg_preload_length 0
		.amdhsa_user_sgpr_kernarg_preload_offset 0
		.amdhsa_user_sgpr_private_segment_size 0
		.amdhsa_uses_dynamic_stack 0
		.amdhsa_enable_private_segment 0
		.amdhsa_system_sgpr_workgroup_id_x 1
		.amdhsa_system_sgpr_workgroup_id_y 0
		.amdhsa_system_sgpr_workgroup_id_z 0
		.amdhsa_system_sgpr_workgroup_info 0
		.amdhsa_system_vgpr_workitem_id 2
		.amdhsa_next_free_vgpr 256
		.amdhsa_next_free_sgpr 102
		.amdhsa_accum_offset 256
		.amdhsa_reserve_vcc 1
		.amdhsa_float_round_mode_32 0
		.amdhsa_float_round_mode_16_64 0
		.amdhsa_float_denorm_mode_32 3
		.amdhsa_float_denorm_mode_16_64 3
		.amdhsa_dx10_clamp 1
		.amdhsa_ieee_mode 1
		.amdhsa_fp16_overflow 0
		.amdhsa_tg_split 0
		.amdhsa_exception_fp_ieee_invalid_op 0
		.amdhsa_exception_fp_denorm_src 0
		.amdhsa_exception_fp_ieee_div_zero 0
		.amdhsa_exception_fp_ieee_overflow 0
		.amdhsa_exception_fp_ieee_underflow 0
		.amdhsa_exception_fp_ieee_inexact 0
		.amdhsa_exception_int_div_zero 0
	.end_amdhsa_kernel

amdhsa.kernels:
  - .agpr_count:     0
    .args:
      - .offset:         0
        .size:           200
        .value_kind:     by_value
      - .offset:         200
        .size:           4
        .value_kind:     hidden_block_count_x
      - .offset:         204
        .size:           4
        .value_kind:     hidden_block_count_y
      - .offset:         208
        .size:           4
        .value_kind:     hidden_block_count_z
      - .offset:         212
        .size:           2
        .value_kind:     hidden_group_size_x
      - .offset:         214
        .size:           2
        .value_kind:     hidden_group_size_y
      - .offset:         216
        .size:           2
        .value_kind:     hidden_group_size_z
      - .offset:         218
        .size:           2
        .value_kind:     hidden_remainder_x
      - .offset:         220
        .size:           2
        .value_kind:     hidden_remainder_y
      - .offset:         222
        .size:           2
        .value_kind:     hidden_remainder_z
      - .offset:         240
        .size:           8
        .value_kind:     hidden_global_offset_x
      - .offset:         248
        .size:           8
        .value_kind:     hidden_global_offset_y
      - .offset:         256
        .size:           8
        .value_kind:     hidden_global_offset_z
      - .offset:         264
        .size:           2
        .value_kind:     hidden_grid_dims
      - .offset:         288
        .size:           8
        .value_kind:     hidden_multigrid_sync_arg
      - .offset:         320
        .size:           4
        .value_kind:     hidden_dynamic_lds_size
    .group_segment_fixed_size: 16
    .kernarg_segment_align: 8
    .kernarg_segment_size: 456
    .language:       OpenCL C
    .language_version:
      - 2
      - 0
    .max_flat_workgroup_size: 512
    .name:           _Z14fwd_megakernel6Params
    .private_segment_fixed_size: 0
    .sgpr_count:     108
    .sgpr_spill_count: 118
    .symbol:         _Z14fwd_megakernel6Params.kd
    .uniform_work_group_size: 1
    .uses_dynamic_stack: false
    .vgpr_count:     256
    .vgpr_spill_count: 0
    .wavefront_size: 64
